# attention work queue: next unit ticket prefetched at unit start (no atomic round trip / store drain at the loop top)
# baseline (speedup 1.0000x reference)
.LBB0_712:
	s_or_b64 exec, exec, s[0:1]
	s_lshr_b64 s[0:1], s[80:81], 1
	s_lshr_b32 s1, s81, 1
	s_mulk_i32 s1, 0x1d10
	s_mul_hi_u32 s2, s0, 0x1d10
	v_readlane_b32 s4, v254, 11
	s_add_i32 s12, s2, s1
	s_mul_i32 s13, s0, 0x1d10
	s_mov_b64 s[0:1], s[76:77]
	s_waitcnt lgkmcnt(0)
	v_cvt_f32_u32_e32 v0, s4
	s_barrier
	s_load_dwordx2 s[0:1], s[0:1], 0xc8
	v_mul_f32_e32 v0, 0xbe99999a, v0
	v_readlane_b32 s5, v254, 12
	v_mul_f32_e32 v1, 0x3fb8aa3b, v0
	s_lshl_b64 s[2:3], s[4:5], 2
	v_fma_f32 v2, v0, s58, -v1
	v_rndne_f32_e32 v3, v1
	v_fmac_f32_e32 v2, 0x32a5705f, v0
	v_sub_f32_e32 v1, v1, v3
	s_waitcnt lgkmcnt(0)
	s_add_u32 s0, s0, s2
	v_add_f32_e32 v1, v1, v2
	v_cvt_i32_f32_e32 v2, v3
	s_addc_u32 s1, s1, s3
	v_mov_b32_e32 v3, 0x20000
	global_load_dword v190, v3, s[0:1] sc1
	v_exp_f32_e32 v1, v1
	s_mov_b32 s0, 0xc2ce8ed0
	v_cmp_ngt_f32_e32 vcc, s0, v0
	s_mov_b32 s0, 0x42b17218
	v_ldexp_f32 v1, v1, v2
	v_cndmask_b32_e32 v1, 0, v1, vcc
	v_cmp_nlt_f32_e32 vcc, s0, v0
	s_lshl_b32 s0, s4, 2
	s_mul_i32 s2, s4, 0x744
	s_mov_b64 s[4:5], s[76:77]
	s_load_dwordx2 s[4:5], s[4:5], 0xc8
	s_cmp_lt_u32 s80, 2
	s_movk_i32 s6, 0x480
	s_cselect_b32 s20, s6, 0x400
	s_lshl_b64 s[6:7], s[66:67], 2
	s_waitcnt lgkmcnt(0)
	s_add_u32 s22, s4, s6
	s_addc_u32 s23, s5, s7
	s_mov_b64 s[4:5], s[76:77]
	s_load_dwordx2 s[4:5], s[4:5], 0xc8
	s_mov_b64 s[8:9], s[76:77]
	s_load_dwordx2 s[8:9], s[8:9], 0xc8
	s_mov_b64 s[10:11], s[76:77]
	s_waitcnt lgkmcnt(0)
	s_add_u32 s21, s4, 0xb800000
	s_load_dwordx2 s[10:11], s[10:11], 0xc8
	s_addc_u32 s24, s5, 0
	s_mov_b64 s[4:5], s[76:77]
	s_load_dwordx2 s[4:5], s[4:5], 0xc8
	s_add_u32 s25, s8, 0xdc00000
	s_addc_u32 s26, s9, 0
	s_mov_b64 s[8:9], s[76:77]
	s_waitcnt lgkmcnt(0)
	s_add_u32 s27, s10, 0xf700000
	s_load_dwordx2 s[8:9], s[8:9], 0x58
	s_addc_u32 s28, s11, 0
	s_add_u32 s30, s4, 0x3100000
	s_addc_u32 s34, s5, 0
	s_mov_b64 s[4:5], s[76:77]
	v_mov_b32_e32 v0, 0x7f800000
	s_mov_b32 s1, s67
	v_cndmask_b32_e32 v0, v0, v1, vcc
	v_mov_b32_e32 v1, 0xbf4ccccd
	s_lshl_b64 s[0:1], s[0:1], 2
	s_load_dwordx2 s[4:5], s[4:5], 0x70
	s_mov_b64 s[10:11], s[76:77]
	v_fmamk_f32 v0, v0, 0x3f19999a, v1
	s_waitcnt lgkmcnt(0)
	s_add_u32 s0, s8, s0
	v_add_f32_e32 v191, 1.0, v0
	s_load_dwordx2 s[10:11], s[10:11], 0x98
	s_addc_u32 s1, s9, s1
	v_mov_b32_e32 v180, v216
	v_mov_b32_e32 v0, v216
	s_mov_b32 s3, s67
	v_writelane_b32 v254, s0, 25
	s_nop 0
	v_mov_b32_e32 v0, v216
	v_writelane_b32 v254, s1, 26
	s_lshl_b64 s[0:1], s[2:3], 2
	s_add_u32 s36, s4, s0
	s_addc_u32 s37, s5, s1
	v_readfirstlane_b32 s0, v0
	v_max_i32_e32 v0, 0xffffffd1, v180
	s_waitcnt lgkmcnt(0)
	s_add_u32 s38, s10, s6
	s_movk_i32 s1, 0x1d1
	v_sub_u32_e32 v0, v0, v180
	s_addc_u32 s39, s11, s7
	v_cmp_gt_i32_e64 s[2:3], s1, v180
	s_ashr_i32 s0, s0, 1
	v_add_u32_e32 v0, 0x1ff, v0
	v_writelane_b32 v254, s2, 27
	s_and_b32 s35, s0, 0xffffffe0
	v_lshrrev_b32_e32 v1, 9, v0
	s_movk_i32 s0, 0x1ff
	v_writelane_b32 v254, s3, 28
	v_add_u32_e32 v1, 1, v1
	v_cmp_lt_u32_e64 s[0:1], s0, v0
	v_and_b32_e32 v192, 0xfffffe, v1
	v_lshlrev_b32_e32 v194, 2, v180
	v_writelane_b32 v254, s0, 29
	v_cmp_eq_u32_e64 s[40:41], 0, v180
	v_lshl_add_u32 v193, v192, 9, v180
	v_writelane_b32 v254, s1, 30
	v_cmp_ne_u32_e64 s[0:1], v1, v192
	v_add_u32_e32 v181, 0x200, v180
	s_nop 0
	v_writelane_b32 v254, s0, 31
	s_nop 1
	v_writelane_b32 v254, s1, 32
	s_nop 0
	v_readlane_b32 s0, v254, 5
	s_nop 1
	v_add_u32_e32 v195, s0, v194
	s_add_u32 s0, s4, s13
	v_writelane_b32 v254, s0, 33
	s_addc_u32 s0, s5, s12
	v_writelane_b32 v254, s0, 34
	v_writelane_b32 v254, s20, 35
	v_writelane_b32 v254, s22, 36
	s_nop 1
	v_writelane_b32 v254, s23, 37
	v_writelane_b32 v254, s21, 38
	v_writelane_b32 v254, s24, 39
	v_writelane_b32 v254, s25, 40
	v_writelane_b32 v254, s26, 41
	v_writelane_b32 v254, s27, 42
	v_writelane_b32 v254, s28, 43
	v_writelane_b32 v254, s30, 44
	v_writelane_b32 v254, s34, 45
	v_writelane_b32 v254, s36, 46
	s_nop 1
	v_writelane_b32 v254, s37, 47
	v_writelane_b32 v254, s38, 48
	s_nop 1
	v_writelane_b32 v254, s39, 49
	v_writelane_b32 v254, s40, 50
	s_nop 1
	v_writelane_b32 v254, s41, 51
	v_writelane_b32 v254, s35, 52
	s_and_saveexec_b64 s[0:1], s[40:41]
	s_cbranch_execz .Lupf_skip
	v_mov_b32_e32 v225, 1
	global_atomic_add v224, v13, v225, s[22:23] sc0
	s_waitcnt vmcnt(0)
.Lupf_skip:
	s_or_b64 exec, exec, s[0:1]
	s_branch .LBB0_717

.LBB0_717:
	s_and_saveexec_b64 s[0:1], s[40:41]
	s_cbranch_execz .LBB0_721
	s_mov_b64 s[4:5], exec
	v_mbcnt_lo_u32_b32 v0, s4, 0
	v_mbcnt_hi_u32_b32 v0, s5, v0
	v_cmp_eq_u32_e32 vcc, 0, v0
	s_and_saveexec_b64 s[2:3], vcc
	s_cbranch_execz .LBB0_720
	s_bcnt1_i32_b64 s4, s[4:5]
	v_mov_b32_e32 v1, v224
	v_mov_b32_e32 v225, s4
	global_atomic_add v224, v13, v225, s[22:23] sc0
.LBB0_720:
	s_or_b64 exec, exec, s[2:3]
	v_readfirstlane_b32 s2, v1
	s_nop 1
	v_add_u32_e32 v0, s2, v0
	ds_write_b32 v13, v0 offset:38912
